# P0 weight-transpose loop software-pipelined: next item decoded and its 8 tile loads (+gain/bias) issued into v64-v97 right after the current tile is in LDS; item state double-buffered in s70-s85
# speedup vs baseline: 1.0023x; 1.0003x over previous
; #define LAS __attribute__((address_space(3)))
; #define LDS_WAIT() asm volatile("s_waitcnt lgkmcnt(0)" ::: "memory")
; __device__ __forceinline__ unsigned f2bf(float f) { unsigned u = __builtin_bit_cast(unsigned, f); return (u + 0x7fffu + ((u >> 16) & 1u)) >> 16; }
; __device__ __forceinline__ void transpose_item(const float* W, int K, int N, bf16_t* WT, LAS float* scr, int item, int lane, const float* gam, const float* bet, float* sdst) {
;     ...
;     for (int i = 0; i < 8; ++i) { const int kk = 8 * i + (lane >> 3), n4 = (lane & 7) * 4;
;         const f32x4 w = *(const f32x4*)(W + (size_t)(k0 + kk) * N + n0 + n4); LAS float* d = scr + kk * 33 + n4; d[0] = w[0]; d[1] = w[1]; d[2] = w[2]; d[3] = w[3]; }
;     if (gam) { scr[64 * 33 + lane] = gam[k0 + lane]; scr[64 * 33 + 64 + lane] = bet[k0 + lane]; }
;     LDS_WAIT(); asm volatile("" ::: "memory");
;     if (gam) {
;         const int n = lane & 31, h = lane >> 5; float sa = 0.f, ta = 0.f;
; #pragma unroll 8
;         for (int i = 0; i < 32; ++i) { const int kk = h * 32 + i; const float w = scr[kk * 33 + n]; const float wg = w * scr[64 * 33 + kk];
;             scr[kk * 33 + n] = wg; sa += bf_lo(f2bf(wg)); ta += w * scr[64 * 33 + 64 + kk]; }
;         sa += __shfl_xor(sa, 32); ta += __shfl_xor(ta, 32);
;         if (lane < 32) { unsafeAtomicAdd(sdst + n0 + lane, sa); unsafeAtomicAdd(sdst + ST_N + n0 + lane, ta); }
;         LDS_WAIT(); asm volatile("" ::: "memory");
;     }
;     const int c = lane & 7;
; #pragma unroll
;     for (int j = 0; j < 4; ++j) { const int n = (lane >> 3) + 8 * j; const LAS float* s = scr + (8 * c) * 33 + n;
; __global__ void __launch_bounds__(NTHR, 2) mega_fwd(Args) {
;     ...
;             constexpr int NI0 = 64 * 256, NI1 = 32 * 64, NI2 = 64 * 128, NI3 = 64 * 512, NI4 = 256 * 128, NI5 = 64 * 8 * ((FOX_IN / 32 + 7) / 8), NI6 = 64 * 128, NI7 = NI3, NI8 = NI4;
;             constexpr int NITOT = NI0 + NI1 + NI2 + NI3 + NI4 + NI5 + NI6 + NI7 + NI8;
;             for (int it = gw; it < NITOT; it += NGW) {
.LBB0_42:
	s_cmp_gt_i32 s36, 0x2e9ff
	v_readlane_b32 s92, v248, 4
	s_cbranch_scc1 .LBB0_87
	s_lshl_b32 s3, s92, 14
	s_add_i32 s8, s3, 0
	s_waitcnt lgkmcnt(0)
	s_add_u32 s6, s48, 0x26b00000
	s_addc_u32 s7, s49, 0
	s_add_u32 s12, s48, 0x1eb00000
	s_addc_u32 s13, s49, 0
	s_add_u32 s14, s48, 0x50000
	s_addc_u32 s15, s49, 0
	s_add_u32 s16, s48, 0x1cb00000
	s_addc_u32 s17, s49, 0
	s_add_u32 s20, s48, 0x16900000
	s_addc_u32 s21, s49, 0
	s_add_u32 s22, s48, 0x30000
	s_addc_u32 s23, s49, 0
	s_add_u32 s24, s48, 0xe900000
	s_addc_u32 s25, s49, 0
	s_add_u32 s26, s48, 0x6900000
	s_addc_u32 s27, s49, 0
	s_add_u32 s28, s48, 0x10000
	v_lshlrev_b32_e32 v2, 3, v4
	s_addc_u32 s29, s49, 0
	v_ashrrev_i32_e32 v8, 3, v4
	v_and_b32_e32 v2, 56, v2
	s_add_u32 s30, s48, 0x4900000
	v_and_b32_e32 v0, 28, v5
	v_mul_u32_u24_e32 v13, 0x84, v2
	v_lshlrev_b32_e32 v14, 2, v8
	v_lshrrev_b32_e32 v15, 5, v4
	s_addc_u32 s31, s49, 0
	v_lshl_add_u32 v3, v0, 2, s8
	v_add_u32_e32 v12, s8, v5
	v_add3_u32 v13, s8, v13, v14
	v_lshl_add_u32 v14, v15, 7, s8
	s_movk_i32 s8, 0x1080
	s_add_u32 s50, s48, 0x4100000
	s_movk_i32 s4, 0x84
	v_mul_lo_u32 v15, v15, s8
	s_addc_u32 s51, s49, 0
	v_mul_lo_u32 v6, v8, s4
	v_and_b32_e32 v7, 31, v4
	v_add_u32_e32 v15, s3, v15
	s_add_u32 s54, s48, 0x100000
	v_lshl_or_b32 v7, v7, 2, v15
	v_add_u32_e32 v16, v3, v6
	v_mbcnt_lo_u32_b32 v3, -1, 0
	s_addc_u32 s55, s49, 0
	v_mov_b32_e32 v1, 0
	v_add_u32_e32 v9, 8, v8
	v_add_u32_e32 v10, 16, v8
	v_add_u32_e32 v11, 24, v8
	v_cmp_gt_i32_e64 s[4:5], 32, v4
	v_ashrrev_i32_e32 v5, 31, v4
	v_add_u32_e32 v14, 0x2100, v14
	v_add_u32_e32 v15, 0, v7
	v_lshlrev_b32_e32 v0, 2, v0
	v_add_u32_e32 v17, 0x420, v16
	v_add_u32_e32 v18, 0x428, v16
	v_add_u32_e32 v19, 0x840, v16
	v_add_u32_e32 v20, 0x848, v16
	v_add_u32_e32 v21, 0xc60, v16
	v_add_u32_e32 v22, 0xc68, v16
	v_add_u32_e32 v23, 0x1080, v16
	v_add_u32_e32 v24, 0x1088, v16
	v_add_u32_e32 v25, 0x14a0, v16
	v_add_u32_e32 v26, 0x14a8, v16
	v_add_u32_e32 v27, 0x18c0, v16
	v_add_u32_e32 v28, 0x18c8, v16
	v_add_u32_e32 v29, 0x1ce0, v16
	v_add_u32_e32 v30, 0x1ce8, v16
	s_movk_i32 s3, 0x7fff
	s_mov_b32 s35, 0xffff0000
	v_lshlrev_b32_e32 v2, 1, v2
	v_mbcnt_hi_u32_b32 v31, -1, v3
	s_mov_b32 s41, s36
	s_mov_b32 s71, 0
	s_branch .LBB0_47
.LBB0_44:
	s_or_b64 exec, exec, s[88:89]
	s_waitcnt lgkmcnt(0)
; #define LAS __attribute__((address_space(3)))
; #define GAS __attribute__((address_space(1)))
; __device__ __forceinline__ unsigned pk2(float lo, float hi) { return f2bf(lo) | (f2bf(hi) << 16); }
; __device__ __forceinline__ void transpose_item(const float* W, int K, int N, bf16_t* WT, LAS float* scr, int item, int lane, const float* gam, const float* bet, float* sdst) {
;     ...
;     for (int i = 0; i < 8; ++i) { const int kk = 8 * i + (lane >> 3), n4 = (lane & 7) * 4;
;         const f32x4 w = *(const f32x4*)(W + (size_t)(k0 + kk) * N + n0 + n4); LAS float* d = scr + kk * 33 + n4; d[0] = w[0]; d[1] = w[1]; d[2] = w[2]; d[3] = w[3]; }
;     if (gam) { scr[64 * 33 + lane] = gam[k0 + lane]; scr[64 * 33 + 64 + lane] = bet[k0 + lane]; }
;     ...
;     for (int j = 0; j < 4; ++j) { const int n = (lane >> 3) + 8 * j; const LAS float* s = scr + (8 * c) * 33 + n;
;         u32x4 o; o.x = pk2(s[0 * 33], s[1 * 33]); o.y = pk2(s[2 * 33], s[3 * 33]); o.z = pk2(s[4 * 33], s[5 * 33]); o.w = pk2(s[6 * 33], s[7 * 33]);
;         *(GAS u32x4*)(WT + (size_t)((n0 + n) >> 8) * ((size_t)K * 256) + (size_t)kb * (256 * 64) + ((n0 + n) & 255) * 64 + 8 * c) = o; }
.LBB0_45:
	ds_read2_b32 v[6:7], v13 offset1:8
	ds_read2_b32 v[36:37], v13 offset0:33 offset1:41
	ds_read2_b32 v[38:39], v13 offset0:66 offset1:74
	ds_read2_b32 v[40:41], v13 offset0:99 offset1:107
	ds_read2_b32 v[42:43], v13 offset0:132 offset1:140
	s_waitcnt lgkmcnt(4)
	v_bfe_u32 v3, v6, 16, 1
	v_add3_u32 v3, v6, v3, s3
	s_waitcnt lgkmcnt(3)
	v_bfe_u32 v6, v36, 16, 1
	v_lshrrev_b32_e32 v3, 16, v3
	v_add3_u32 v6, v36, v6, s3
	ds_read2_b32 v[44:45], v13 offset0:165 offset1:173
	v_and_or_b32 v32, v6, s35, v3
	s_waitcnt lgkmcnt(3)
	v_bfe_u32 v3, v38, 16, 1
	v_add3_u32 v3, v38, v3, s3
	s_waitcnt lgkmcnt(2)
	v_bfe_u32 v6, v40, 16, 1
	ds_read2_b32 v[46:47], v13 offset0:198 offset1:206
	v_lshrrev_b32_e32 v3, 16, v3
	v_add3_u32 v6, v40, v6, s3
	ds_read2_b32 v[48:49], v13 offset0:231 offset1:239
	v_and_or_b32 v33, v6, s35, v3
	s_waitcnt lgkmcnt(3)
	v_bfe_u32 v3, v42, 16, 1
	v_add3_u32 v3, v42, v3, s3
	s_waitcnt lgkmcnt(2)
	v_bfe_u32 v6, v44, 16, 1
	v_lshrrev_b32_e32 v3, 16, v3
	v_add3_u32 v6, v44, v6, s3
	v_and_or_b32 v34, v6, s35, v3
	s_waitcnt lgkmcnt(1)
	v_bfe_u32 v3, v46, 16, 1
	v_add3_u32 v3, v46, v3, s3
	s_waitcnt lgkmcnt(0)
	v_bfe_u32 v6, v48, 16, 1
	s_ashr_i32 s81, s80, 31
	v_lshrrev_b32_e32 v3, 16, v3
	v_add3_u32 v6, v48, v6, s3
	s_lshl_b64 s[38:39], s[80:81], 15
	v_and_or_b32 v35, v6, s35, v3
	v_add_u32_e32 v3, s85, v8
	s_add_u32 s38, s82, s38
	v_lshrrev_b32_e32 v6, 8, v3
	s_addc_u32 s39, s83, s39
	v_mul_hi_i32_i24_e32 v51, s84, v6
	v_mul_i32_i24_e32 v50, s84, v6
	v_lshlrev_b32_e32 v3, 7, v3
	v_lshl_add_u64 v[50:51], v[50:51], 1, s[38:39]
	v_and_b32_e32 v52, 0x7f80, v3
	v_mov_b32_e32 v53, v1
	v_bfe_u32 v6, v7, 16, 1
	v_lshl_add_u64 v[50:51], v[50:51], 0, v[52:53]
	v_mov_b32_e32 v3, v1
	v_add3_u32 v6, v7, v6, s3
	v_bfe_u32 v7, v37, 16, 1
	v_lshl_add_u64 v[50:51], v[50:51], 0, v[2:3]
	v_lshrrev_b32_e32 v6, 16, v6
	v_add3_u32 v7, v37, v7, s3
	global_store_dwordx4 v[50:51], v[32:35], off
	v_add_u32_e32 v36, s85, v9
	v_mov_b32_e32 v37, v1
	v_and_or_b32 v32, v7, s35, v6
	v_bfe_u32 v6, v39, 16, 1
	v_add3_u32 v6, v39, v6, s3
	v_bfe_u32 v7, v41, 16, 1
	v_lshrrev_b32_e32 v6, 16, v6
	v_add3_u32 v7, v41, v7, s3
	v_and_or_b32 v33, v7, s35, v6
	v_bfe_u32 v6, v43, 16, 1
	v_add3_u32 v6, v43, v6, s3
	v_bfe_u32 v7, v45, 16, 1
	v_lshrrev_b32_e32 v6, 16, v6
	v_add3_u32 v7, v45, v7, s3
	v_and_or_b32 v34, v7, s35, v6
	v_bfe_u32 v6, v47, 16, 1
	v_add3_u32 v6, v47, v6, s3
	v_bfe_u32 v7, v49, 16, 1
	v_lshrrev_b32_e32 v6, 16, v6
	v_add3_u32 v7, v49, v7, s3
	v_and_or_b32 v35, v7, s35, v6
	v_lshrrev_b32_e32 v6, 8, v36
	v_mul_hi_i32_i24_e32 v7, s84, v6
	v_mul_i32_i24_e32 v6, s84, v6
	v_lshlrev_b32_e32 v36, 7, v36
	v_lshl_add_u64 v[6:7], v[6:7], 1, s[38:39]
	v_and_b32_e32 v36, 0x7f80, v36
	v_lshl_add_u64 v[6:7], v[6:7], 0, v[36:37]
	ds_read2_b32 v[38:39], v13 offset0:16 offset1:24
	v_lshl_add_u64 v[6:7], v[6:7], 0, v[2:3]
	global_store_dwordx4 v[6:7], v[32:35], off
	ds_read2_b32 v[6:7], v13 offset0:49 offset1:57
	ds_read2_b32 v[36:37], v13 offset0:82 offset1:90
	ds_read2_b32 v[40:41], v13 offset0:115 offset1:123
	s_waitcnt lgkmcnt(3)
	v_bfe_u32 v32, v38, 16, 1
	v_add3_u32 v32, v38, v32, s3
	s_waitcnt lgkmcnt(2)
	v_bfe_u32 v33, v6, 16, 1
	ds_read2_b32 v[42:43], v13 offset0:148 offset1:156
	v_lshrrev_b32_e32 v32, 16, v32
	v_add3_u32 v6, v6, v33, s3
	ds_read2_b32 v[44:45], v13 offset0:181 offset1:189
	v_and_or_b32 v32, v6, s35, v32
	s_waitcnt lgkmcnt(3)
	v_bfe_u32 v6, v36, 16, 1
	v_add3_u32 v6, v36, v6, s3
	s_waitcnt lgkmcnt(2)
	v_bfe_u32 v33, v40, 16, 1
	ds_read2_b32 v[46:47], v13 offset0:214 offset1:222
	v_lshrrev_b32_e32 v6, 16, v6
	v_add3_u32 v33, v40, v33, s3
	ds_read2_b32 v[48:49], v13 offset0:247 offset1:255
	v_and_or_b32 v33, v33, s35, v6
	s_waitcnt lgkmcnt(3)
	v_bfe_u32 v6, v42, 16, 1
	v_add3_u32 v6, v42, v6, s3
	s_waitcnt lgkmcnt(2)
	v_bfe_u32 v34, v44, 16, 1
	v_lshrrev_b32_e32 v6, 16, v6
	v_add3_u32 v34, v44, v34, s3
	v_and_or_b32 v34, v34, s35, v6
	s_waitcnt lgkmcnt(1)
	v_bfe_u32 v6, v46, 16, 1
	v_add3_u32 v6, v46, v6, s3
	s_waitcnt lgkmcnt(0)
	v_bfe_u32 v35, v48, 16, 1
	v_lshrrev_b32_e32 v6, 16, v6
	v_add3_u32 v35, v48, v35, s3
	v_and_or_b32 v35, v35, s35, v6
	v_add_u32_e32 v6, s85, v10
	v_lshrrev_b32_e32 v36, 8, v6
	v_mul_hi_i32_i24_e32 v51, s84, v36
	v_mul_i32_i24_e32 v50, s84, v36
	v_lshlrev_b32_e32 v6, 7, v6
	v_lshl_add_u64 v[50:51], v[50:51], 1, s[38:39]
	v_and_b32_e32 v52, 0x7f80, v6
	v_lshl_add_u64 v[50:51], v[50:51], 0, v[52:53]
	v_lshl_add_u64 v[50:51], v[50:51], 0, v[2:3]
	v_bfe_u32 v6, v39, 16, 1
	global_store_dwordx4 v[50:51], v[32:35], off
	v_add3_u32 v6, v39, v6, s3
	v_lshrrev_b32_e32 v6, 16, v6
	v_bfe_u32 v32, v7, 16, 1
	v_add3_u32 v7, v7, v32, s3
	v_and_or_b32 v32, v7, s35, v6
	v_bfe_u32 v6, v37, 16, 1
	v_add3_u32 v6, v37, v6, s3
	v_bfe_u32 v7, v41, 16, 1
	v_lshrrev_b32_e32 v6, 16, v6
	v_add3_u32 v7, v41, v7, s3
	v_and_or_b32 v33, v7, s35, v6
	v_bfe_u32 v6, v43, 16, 1
	v_add3_u32 v6, v43, v6, s3
	v_bfe_u32 v7, v45, 16, 1
	v_lshrrev_b32_e32 v6, 16, v6
	v_add3_u32 v7, v45, v7, s3
	v_and_or_b32 v34, v7, s35, v6
	v_bfe_u32 v6, v47, 16, 1
	v_add3_u32 v6, v47, v6, s3
	v_bfe_u32 v7, v49, 16, 1
	v_lshrrev_b32_e32 v6, 16, v6
	v_add3_u32 v7, v49, v7, s3
	v_add_u32_e32 v36, s85, v11
	v_and_or_b32 v35, v7, s35, v6
	v_lshrrev_b32_e32 v6, 8, v36
	v_mul_hi_i32_i24_e32 v7, s84, v6
	v_mul_i32_i24_e32 v6, s84, v6
	v_lshlrev_b32_e32 v36, 7, v36
	v_lshl_add_u64 v[6:7], v[6:7], 1, s[38:39]
	v_and_b32_e32 v36, 0x7f80, v36
	v_mov_b32_e32 v37, v1
	v_lshl_add_u64 v[6:7], v[6:7], 0, v[36:37]
	v_lshl_add_u64 v[6:7], v[6:7], 0, v[2:3]
	global_store_dwordx4 v[6:7], v[32:35], off
	s_waitcnt lgkmcnt(0)
.LBB0_46:
	s_cmp_gt_i32 s41, 0x2e9ff
	s_cbranch_scc1 .LBB0_87
.Lp0_top:
	s_mov_b32 s70, s87
	s_mov_b64 s[72:73], s[8:9]
	s_mov_b64 s[76:77], s[60:61]
	s_mov_b64 s[78:79], s[68:69]
	s_mov_b32 s80, s66
	s_mov_b64 s[82:83], s[58:59]
	s_mov_b32 s84, s56
	s_mov_b32 s85, s62
	s_mov_b32 s71, 1
	s_cmp_eq_u32 s70, 0
	s_cbranch_scc1 .Lp0_adv
	s_waitcnt vmcnt(0)
	ds_write2_b32 v16, v64, v65 offset1:1
	ds_write2_b32 v16, v66, v67 offset0:2 offset1:3
	ds_write2_b32 v17, v68, v69 offset1:1
	ds_write2_b32 v18, v70, v71 offset1:1
	ds_write2_b32 v19, v72, v73 offset1:1
	ds_write2_b32 v20, v74, v75 offset1:1
	ds_write2_b32 v21, v76, v77 offset1:1
	ds_write2_b32 v22, v78, v79 offset1:1
	ds_write2_b32 v23, v80, v81 offset1:1
	ds_write2_b32 v24, v82, v83 offset1:1
	ds_write2_b32 v25, v84, v85 offset1:1
	ds_write2_b32 v26, v86, v87 offset1:1
	ds_write2_b32 v27, v88, v89 offset1:1
	ds_write2_b32 v28, v90, v91 offset1:1
	ds_write2_b32 v29, v92, v93 offset1:1
	ds_write2_b32 v30, v94, v95 offset1:1
	s_cmp_eq_u64 s[72:73], 0
	s_cbranch_scc1 .Lp0_adv
	ds_write2st64_b32 v12, v96, v97 offset0:33 offset1:34

; #define LAS __attribute__((address_space(3)))
; __device__ __forceinline__ void transpose_item(const float* W, int K, int N, bf16_t* WT, LAS float* scr, int item, int lane, const float* gam, const float* bet, float* sdst) {
;     const int nblk = N / 32, nbg = (nblk + 7) >> 3, g64 = item >> 6, r = item & 63;
;     const int nb = (g64 % nbg) * 8 + (r & 7), kb = (g64 / nbg) * 8 + (r >> 3), k0 = 64 * kb, n0 = 32 * nb;
;     if (nb >= nblk) return;
; #pragma unroll
;     for (int i = 0; i < 8; ++i) { const int kk = 8 * i + (lane >> 3), n4 = (lane & 7) * 4;
;         const f32x4 w = *(const f32x4*)(W + (size_t)(k0 + kk) * N + n0 + n4); LAS float* d = scr + kk * 33 + n4; d[0] = w[0]; d[1] = w[1]; d[2] = w[2]; d[3] = w[3]; }
;     if (gam) { scr[64 * 33 + lane] = gam[k0 + lane]; scr[64 * 33 + 64 + lane] = bet[k0 + lane]; }
.LBB0_79:
	s_lshr_b32 s38, s43, 5
	s_add_i32 s39, s38, 7
	s_lshr_b32 s39, s39, 3
	v_cvt_f32_u32_e32 v3, s39
	s_sub_i32 s57, 0, s39
	s_ashr_i32 s52, s44, 6
	s_abs_i32 s53, s52
	v_rcp_iflag_f32_e32 v3, v3
	s_ashr_i32 s45, s44, 31
	v_mul_f32_e32 v3, 0x4f7ffffe, v3
	v_cvt_u32_f32_e32 v3, v3
	s_nop 0
	v_readfirstlane_b32 s62, v3
	s_mul_i32 s57, s57, s62
	s_mul_hi_u32 s57, s62, s57
	s_add_i32 s62, s62, s57
	s_mul_hi_u32 s57, s53, s62
	s_mul_i32 s62, s57, s39
	s_sub_i32 s53, s53, s62
	s_add_i32 s63, s57, 1
	s_sub_i32 s62, s53, s39
	s_cmp_ge_u32 s53, s39
	s_cselect_b32 s57, s63, s57
	s_cselect_b32 s53, s62, s53
	s_add_i32 s62, s57, 1
	s_cmp_ge_u32 s53, s39
	s_cselect_b32 s53, s62, s57
	s_xor_b32 s53, s53, s45
	s_sub_i32 s45, s53, s45
	s_mul_i32 s39, s45, s39
	s_sub_i32 s39, s52, s39
	s_lshl_b32 s39, s39, 3
	s_and_b32 s52, s44, 7
	s_or_b32 s52, s39, s52
	s_cmp_ge_i32 s52, s38
	s_cbranch_scc1 .Lp0_skip
	s_lshl_b32 s38, s45, 3
	s_bfe_u32 s39, s44, 0x30003
	s_lshl_b32 s62, s52, 5
	s_or_b32 s66, s38, s39
	s_ashr_i32 s63, s62, 31
	s_lshl_b32 s44, s66, 6
	s_lshl_b64 s[68:69], s[62:63], 2
	s_waitcnt lgkmcnt(0)
	s_add_u32 s52, s64, s68
	v_add_u32_e32 v3, s44, v8
	s_addc_u32 s53, s65, s69
	v_add_u32_e32 v40, s44, v10
	v_add_u32_e32 v48, 32, v3
	v_lshl_add_u64 v[6:7], s[52:53], 0, v[0:1]
	v_mad_u64_u32 v[32:33], s[52:53], v3, s43, 0
	v_ashrrev_i32_e32 v43, 31, v40
	v_mad_u64_u32 v[40:41], s[52:53], v40, s43, 0
	v_ashrrev_i32_e32 v51, 31, v48
	v_mad_u64_u32 v[48:49], s[52:53], v48, s43, 0
	v_ashrrev_i32_e32 v35, 31, v3
	v_mov_b32_e32 v34, v33
	v_mov_b32_e32 v42, v41
	v_mov_b32_e32 v50, v49
	v_mad_u64_u32 v[34:35], s[52:53], v35, s43, v[34:35]
	v_mad_u64_u32 v[42:43], s[52:53], v43, s43, v[42:43]
	v_mad_u64_u32 v[50:51], s[52:53], v51, s43, v[50:51]
	v_mov_b32_e32 v33, v34
	v_add_u32_e32 v34, s44, v9
	v_mov_b32_e32 v41, v42
	v_add_u32_e32 v42, s44, v11
	v_mov_b32_e32 v49, v50
	v_add_u32_e32 v50, 40, v3
	v_add_u32_e32 v56, 48, v3
	v_add_u32_e32 v3, 56, v3
	v_ashrrev_i32_e32 v37, 31, v34
	v_mad_u64_u32 v[34:35], s[52:53], v34, s43, 0
	v_ashrrev_i32_e32 v45, 31, v42
	v_mad_u64_u32 v[42:43], s[52:53], v42, s43, 0
	v_ashrrev_i32_e32 v53, 31, v50
	v_mad_u64_u32 v[50:51], s[52:53], v50, s43, 0
	v_ashrrev_i32_e32 v59, 31, v56
	v_mad_u64_u32 v[56:57], s[52:53], v56, s43, 0
	v_mad_u64_u32 v[60:61], s[52:53], v3, s43, 0
	v_mov_b32_e32 v36, v35
	v_mov_b32_e32 v44, v43
	v_mov_b32_e32 v52, v51
	v_mov_b32_e32 v58, v57
	v_ashrrev_i32_e32 v63, 31, v3
	v_mov_b32_e32 v62, v61
	v_mad_u64_u32 v[36:37], s[52:53], v37, s43, v[36:37]
	v_mad_u64_u32 v[44:45], s[52:53], v45, s43, v[44:45]
	v_mad_u64_u32 v[52:53], s[52:53], v53, s43, v[52:53]
	v_mad_u64_u32 v[58:59], s[52:53], v59, s43, v[58:59]
	v_mad_u64_u32 v[62:63], s[52:53], v63, s43, v[62:63]
	v_mov_b32_e32 v35, v36
	v_mov_b32_e32 v43, v44
	v_mov_b32_e32 v51, v52
	v_mov_b32_e32 v57, v58
	v_mov_b32_e32 v61, v62
	v_lshl_add_u64 v[32:33], v[32:33], 2, v[6:7]
	v_lshl_add_u64 v[36:37], v[34:35], 2, v[6:7]
	v_lshl_add_u64 v[40:41], v[40:41], 2, v[6:7]
	v_lshl_add_u64 v[44:45], v[42:43], 2, v[6:7]
	v_lshl_add_u64 v[48:49], v[48:49], 2, v[6:7]
	v_lshl_add_u64 v[52:53], v[50:51], 2, v[6:7]
	v_lshl_add_u64 v[56:57], v[56:57], 2, v[6:7]
	v_lshl_add_u64 v[6:7], v[60:61], 2, v[6:7]
	global_load_dwordx4 v[64:67], v[32:33], off
	global_load_dwordx4 v[68:71], v[36:37], off
	global_load_dwordx4 v[72:75], v[40:41], off
	global_load_dwordx4 v[76:79], v[44:45], off
	global_load_dwordx4 v[80:83], v[48:49], off
	global_load_dwordx4 v[84:87], v[52:53], off
	global_load_dwordx4 v[88:91], v[56:57], off
	global_load_dwordx4 v[92:95], v[6:7], off
	s_cmp_eq_u64 s[8:9], 0
	s_cbranch_scc1 .Lp0_nogb
	v_add_u32_e32 v6, s44, v4
	v_ashrrev_i32_e32 v7, 31, v6
	v_lshlrev_b64 v[6:7], 2, v[6:7]
	v_lshl_add_u64 v[32:33], s[8:9], 0, v[6:7]
	v_lshl_add_u64 v[6:7], s[10:11], 0, v[6:7]
	global_load_dword v96, v[32:33], off
	global_load_dword v97, v[6:7], off
; __device__ __forceinline__ unsigned f2bf(float f) { unsigned u = __builtin_bit_cast(unsigned, f); return (u + 0x7fffu + ((u >> 16) & 1u)) >> 16; }
; __device__ __forceinline__ void transpose_item(const float* W, int K, int N, bf16_t* WT, LAS float* scr, int item, int lane, const float* gam, const float* bet, float* sdst) {
;     ...
;     if (gam) {
;         const int n = lane & 31, h = lane >> 5; float sa = 0.f, ta = 0.f;
; #pragma unroll 8
;         for (int i = 0; i < 32; ++i) { const int kk = h * 32 + i; const float w = scr[kk * 33 + n]; const float wg = w * scr[64 * 33 + kk];
;             scr[kk * 33 + n] = wg; sa += bf_lo(f2bf(wg)); ta += w * scr[64 * 33 + 64 + kk]; }
;         sa += __shfl_xor(sa, 32); ta += __shfl_xor(ta, 32);
;         if (lane < 32) { unsafeAtomicAdd(sdst + n0 + lane, sa); unsafeAtomicAdd(sdst + ST_N + n0 + lane, ta); }
; __global__ void __launch_bounds__(NTHR, 2) mega_fwd(Args) {
;     ...
;             for (int it = gw; it < NITOT; it += NGW) {
.Lp0_nogb:
	s_mov_b32 s87, 1
	s_branch .Lp0_issued
.Lp0_skip:
	s_waitcnt lgkmcnt(0)
	s_mov_b32 s87, 0
.Lp0_issued:
	s_cmp_eq_u32 s71, 0
	s_cbranch_scc1 .Lp0_top
.Lp0_process:
	s_cmp_eq_u32 s70, 0
	s_cbranch_scc1 .LBB0_46
	s_waitcnt lgkmcnt(0)
	s_cmp_eq_u64 s[72:73], 0
	s_cbranch_scc1 .LBB0_45
	v_mov_b32_e32 v6, 0
	s_mov_b32 s86, 0
	v_mov_b32_e32 v3, v15
	v_mov_b32_e32 v7, v6
.LBB0_84:
	v_add_u32_e32 v42, s86, v14
	ds_read2_b32 v[32:33], v3 offset1:33
	ds_read2_b32 v[34:35], v3 offset0:66 offset1:99
	ds_read2_b32 v[36:37], v3 offset0:132 offset1:165
	ds_read2_b32 v[38:39], v3 offset0:198 offset1:231
	ds_read_b128 v[44:47], v42
	ds_read_b128 v[48:51], v42 offset:16
	ds_read_b128 v[52:55], v42 offset:256
	ds_read_b128 v[56:59], v42 offset:272
	s_add_i32 s86, s86, 32
	s_cmpk_eq_i32 s86, 0x80
	s_waitcnt lgkmcnt(0)
	v_mul_f32_e32 v40, v32, v44
	v_mul_f32_e32 v60, v32, v52
	ds_write_b32 v3, v40
	v_bfe_u32 v41, v40, 16, 1
	v_add3_u32 v41, v40, v41, s3
	v_and_b32_e32 v61, 0xffff0000, v41
	v_pk_add_f32 v[6:7], v[6:7], v[60:61]
	v_mul_f32_e32 v62, v33, v45
	v_mul_f32_e32 v60, v33, v53
	ds_write_b32 v3, v62 offset:132
	v_bfe_u32 v63, v62, 16, 1
	v_add3_u32 v63, v62, v63, s3
	v_and_b32_e32 v61, 0xffff0000, v63
	v_pk_add_f32 v[6:7], v[6:7], v[60:61]
	v_mul_f32_e32 v40, v34, v46
	v_mul_f32_e32 v60, v34, v54
	ds_write_b32 v3, v40 offset:264
	v_bfe_u32 v41, v40, 16, 1
	v_add3_u32 v41, v40, v41, s3
	v_and_b32_e32 v61, 0xffff0000, v41
	v_pk_add_f32 v[6:7], v[6:7], v[60:61]
	v_mul_f32_e32 v62, v35, v47
	v_mul_f32_e32 v60, v35, v55
	ds_write_b32 v3, v62 offset:396
	v_bfe_u32 v63, v62, 16, 1
	v_add3_u32 v63, v62, v63, s3
	v_and_b32_e32 v61, 0xffff0000, v63
	v_pk_add_f32 v[6:7], v[6:7], v[60:61]
	v_mul_f32_e32 v40, v36, v48
	v_mul_f32_e32 v60, v36, v56
	ds_write_b32 v3, v40 offset:528
	v_bfe_u32 v41, v40, 16, 1
	v_add3_u32 v41, v40, v41, s3
	v_and_b32_e32 v61, 0xffff0000, v41
	v_pk_add_f32 v[6:7], v[6:7], v[60:61]
	v_mul_f32_e32 v62, v37, v49
	v_mul_f32_e32 v60, v37, v57
	ds_write_b32 v3, v62 offset:660
	v_bfe_u32 v63, v62, 16, 1
	v_add3_u32 v63, v62, v63, s3
	v_and_b32_e32 v61, 0xffff0000, v63
	v_pk_add_f32 v[6:7], v[6:7], v[60:61]
	v_mul_f32_e32 v40, v38, v50
	v_mul_f32_e32 v60, v38, v58
	ds_write_b32 v3, v40 offset:792
	v_bfe_u32 v41, v40, 16, 1
	v_add3_u32 v41, v40, v41, s3
	v_and_b32_e32 v61, 0xffff0000, v41
	v_pk_add_f32 v[6:7], v[6:7], v[60:61]
	v_mul_f32_e32 v62, v39, v51
	v_mul_f32_e32 v60, v39, v59
	ds_write_b32 v3, v62 offset:924
	v_bfe_u32 v63, v62, 16, 1
	v_add3_u32 v63, v62, v63, s3
	v_and_b32_e32 v61, 0xffff0000, v63
	v_pk_add_f32 v[6:7], v[6:7], v[60:61]
	v_add_u32_e32 v3, 0x420, v3
	s_cbranch_scc0 .LBB0_84
	v_and_b32_e32 v32, 64, v31
	v_xor_b32_e32 v3, 32, v31
	v_add_u32_e32 v32, 64, v32
	v_cmp_lt_i32_e32 vcc, v3, v32
	s_nop 1
	v_cndmask_b32_e32 v3, v31, v3, vcc
	v_lshlrev_b32_e32 v32, 2, v3
	ds_bpermute_b32 v3, v32, v7
	ds_bpermute_b32 v32, v32, v6
	s_and_saveexec_b64 s[88:89], s[4:5]
	s_cbranch_execz .LBB0_44
	s_add_u32 s38, s76, s78
	s_addc_u32 s39, s77, s79
	s_waitcnt lgkmcnt(0)
	v_add_f32_e32 v32, v6, v32
	v_add_f32_e32 v3, v7, v3
	v_lshl_add_u64 v[6:7], v[4:5], 2, s[38:39]
	global_atomic_add_f32 v[6:7], v3, off
	v_add_co_u32_e32 v6, vcc, 0x10000, v6
	s_nop 1
	v_addc_co_u32_e32 v7, vcc, 0, v7, vcc
	global_atomic_add_f32 v[6:7], v32, off
	s_branch .LBB0_44
